# attention units permuted so the 32 query blocks of a head run on one XCD (K/V halo rows shared in L2); plus previous wait fix
# speedup vs baseline: 1.0250x; 1.0057x over previous
; #define ATTN_QLOAD(W) do { const bf16_t* qr_ = Qb + ((size_t)((W).b * 24 + (W).hd) * SEQ + (size_t)((W).r * (W).L + (W).i0 + 32 * wave + l31)) * 64; \
;         _Pragma("unroll") for (int ks_ = 0; ks_ < 4; ++ks_) qv[ks_] = *(const u32x4*)(qr_ + 16 * ks_ + 8 * h); } while (0)
; __device__ __forceinline__ void attn_issue(const AUnit& w, const bf16_t* Qb, const bf16_t* Kb, const bf16_t* Vb, int tid, int wave, int lane, u32x4 (&kv)[6], u32x4 (&vv)[6]) {
;     const int ch = tid & 7;
; #pragma unroll
;     for (int i = 0; i < 6; ++i) { const int row = (tid + 512 * i) >> 3; int pk = w.i0 - 64 + row; pk = pk < 0 ? 0 : (pk >= w.L ? w.L - 1 : pk);
;         const size_t off = ((size_t)(w.b * 24 + w.hd) * SEQ + (size_t)(w.r * w.L + pk)) * 64 + ch * 8; kv[i] = *(const u32x4*)(Kb + off); vv[i] = *(const u32x4*)(Vb + off); }
; }
; template <bool FUSED> __device__ __forceinline__ void attn_phase(const Args& a, LAS unsigned char* lds, int tid, int lane, int wave) {
;     ...
;     if (u < NU) { const AUnit w0 = attn_decode(u, HD0, NH); attn_issue(w0, Qb, Kb, Vb, tid, wave, lane, kv, vv); ATTN_QLOAD(w0); }
.LBB0_277:
	s_or_b64 exec, exec, s[0:1]
	s_add_u32 s87, s52, 0xf00000
	s_addc_u32 s88, s53, 0
	s_add_u32 s58, s52, 0x26000000
	s_addc_u32 s59, s53, 0
	s_add_u32 s60, s52, 0x32000000
	s_addc_u32 s61, s53, 0
	s_add_u32 s62, s52, 0xf40000
	s_addc_u32 s63, s53, 0
	s_cmpk_lt_i32 s2, 0x1000
	s_waitcnt lgkmcnt(0)
	v_mov_b32_e32 v0, v186
	v_mov_b32_e32 v1, v178
	s_cselect_b64 s[64:65], -1, 0
	s_cmpk_gt_i32 s2, 0xfff
	s_barrier
	s_cbranch_scc1 .LBB0_286
	s_and_b32 s93, s2, 7
	s_lshl_b32 s93, s93, 5
	s_bfe_u32 s94, s2, 0x50003
	s_or_b32 s93, s93, s94
	s_andn2_b32 s94, s2, 0xff
	s_or_b32 s93, s93, s94
	s_cmpk_eq_i32 s54, 0x100
	s_cselect_b32 s93, s93, s2
	s_ashr_i32 s1, s93, 5
	s_lshr_b32 s4, s1, 28
	s_add_i32 s4, s1, s4
	s_and_b32 s4, s4, -16
	s_sub_i32 s1, s1, s4
	s_add_i32 s1, s1, 8
	s_ashr_i32 s5, s1, 2
	s_and_b32 s5, s5, -2
	s_lshr_b32 s6, 32, s5
	s_and_b32 s0, s93, 31
	s_lshr_b32 s7, 0x2000, s5
	s_sub_i32 s5, 5, s5
	s_add_i32 s6, s6, -1
	s_lshr_b32 s5, s0, s5
	s_and_b32 s0, s6, s0
	s_ashr_i32 s4, s93, 31
	s_lshl_b32 s6, s0, 8
	s_lshr_b32 s4, s4, 23
	v_lshlrev_b32_e32 v2, 3, v1
	v_ashrrev_i32_e32 v9, 3, v1
	s_sub_i32 s8, s6, 64
	s_add_i32 s4, s93, s4
	v_and_b32_e32 v144, 56, v2
	v_add_u32_e32 v2, s8, v9
	s_add_i32 s9, s7, -1
	s_ashr_i32 s4, s4, 9
	v_min_i32_e32 v3, s9, v2
	v_cmp_lt_i32_e32 vcc, -1, v2
	s_mul_i32 s4, s4, 24
	s_mul_i32 s7, s5, s7
	v_cndmask_b32_e32 v2, 0, v3, vcc
	s_add_i32 s0, s1, s4
	v_add_u32_e32 v2, s7, v2
	s_ashr_i32 s1, s0, 31
	v_ashrrev_i32_e32 v3, 31, v2
	s_lshl_b64 s[4:5], s[0:1], 19
	v_lshlrev_b64 v[2:3], 6, v[2:3]
	v_lshl_add_u64 v[2:3], v[2:3], 0, s[4:5]
	v_or_b32_e32 v2, v2, v144
	v_lshlrev_b64 v[2:3], 1, v[2:3]
	v_lshl_add_u64 v[4:5], s[58:59], 0, v[2:3]
	v_lshl_add_u64 v[2:3], s[60:61], 0, v[2:3]
	global_load_dwordx4 v[64:67], v[4:5], off
	global_load_dwordx4 v[68:71], v[2:3], off
	v_add_u32_e32 v2, 0x200, v1
	v_ashrrev_i32_e32 v10, 3, v2
	v_add_u32_e32 v2, s8, v10
	v_min_i32_e32 v3, s9, v2
	v_cmp_lt_i32_e32 vcc, -1, v2
	v_and_b32_e32 v7, 31, v0
	s_lshl_b64 s[0:1], s[0:1], 20
	v_cndmask_b32_e32 v2, 0, v3, vcc
	v_add_u32_e32 v2, s7, v2
	v_ashrrev_i32_e32 v3, 31, v2
	v_lshlrev_b64 v[2:3], 6, v[2:3]
	v_lshl_add_u64 v[2:3], v[2:3], 0, s[4:5]
	v_or_b32_e32 v2, v2, v144
	v_lshlrev_b64 v[2:3], 1, v[2:3]
	v_lshl_add_u64 v[4:5], s[58:59], 0, v[2:3]
	v_lshl_add_u64 v[2:3], s[60:61], 0, v[2:3]
	global_load_dwordx4 v[72:75], v[4:5], off
	global_load_dwordx4 v[76:79], v[2:3], off
	v_add_u32_e32 v2, 0x400, v1
	v_ashrrev_i32_e32 v11, 3, v2
	v_add_u32_e32 v2, s8, v11
	v_min_i32_e32 v3, s9, v2
	v_cmp_lt_i32_e32 vcc, -1, v2
	v_ashrrev_i32_e32 v8, 5, v0
	v_lshlrev_b32_e32 v148, 3, v8
	v_cndmask_b32_e32 v2, 0, v3, vcc
	v_add_u32_e32 v2, s7, v2
	v_ashrrev_i32_e32 v3, 31, v2
	v_lshlrev_b64 v[2:3], 6, v[2:3]
	v_lshl_add_u64 v[2:3], v[2:3], 0, s[4:5]
	v_or_b32_e32 v2, v2, v144
	v_lshlrev_b64 v[2:3], 1, v[2:3]
	v_lshl_add_u64 v[4:5], s[58:59], 0, v[2:3]
	v_lshl_add_u64 v[2:3], s[60:61], 0, v[2:3]
	global_load_dwordx4 v[80:83], v[4:5], off
	global_load_dwordx4 v[84:87], v[2:3], off
	v_add_u32_e32 v2, 0x600, v1
	v_ashrrev_i32_e32 v12, 3, v2
	v_add_u32_e32 v2, s8, v12
	v_min_i32_e32 v3, s9, v2
	v_cmp_lt_i32_e32 vcc, -1, v2
	v_ashrrev_i32_e32 v149, 31, v148
	v_lshrrev_b32_e32 v6, 2, v0
	v_cndmask_b32_e32 v2, 0, v3, vcc
	v_add_u32_e32 v2, s7, v2
	v_ashrrev_i32_e32 v3, 31, v2
	v_lshlrev_b64 v[2:3], 6, v[2:3]
	v_lshl_add_u64 v[2:3], v[2:3], 0, s[4:5]
	v_or_b32_e32 v2, v2, v144
	v_lshlrev_b64 v[2:3], 1, v[2:3]
	v_lshl_add_u64 v[4:5], s[58:59], 0, v[2:3]
	v_lshl_add_u64 v[2:3], s[60:61], 0, v[2:3]
	global_load_dwordx4 v[96:99], v[4:5], off
	global_load_dwordx4 v[104:107], v[2:3], off
	v_add_u32_e32 v2, 0x800, v1
	v_ashrrev_i32_e32 v13, 3, v2
	v_add_u32_e32 v2, s8, v13
	v_min_i32_e32 v3, s9, v2
	v_cmp_lt_i32_e32 vcc, -1, v2
	v_lshl_add_u32 v15, v8, 4, 0
	v_mov_b32_e32 v147, 0
	v_cndmask_b32_e32 v2, 0, v3, vcc
	v_add_u32_e32 v2, s7, v2
	v_ashrrev_i32_e32 v3, 31, v2
	v_lshlrev_b64 v[2:3], 6, v[2:3]
	v_lshl_add_u64 v[2:3], v[2:3], 0, s[4:5]
	v_or_b32_e32 v2, v2, v144
	v_lshlrev_b64 v[2:3], 1, v[2:3]
	v_lshl_add_u64 v[4:5], s[58:59], 0, v[2:3]
	v_lshl_add_u64 v[2:3], s[60:61], 0, v[2:3]
	global_load_dwordx4 v[112:115], v[4:5], off
	global_load_dwordx4 v[116:119], v[2:3], off
	v_add_u32_e32 v2, 0xa00, v1
	v_ashrrev_i32_e32 v14, 3, v2
	v_add_u32_e32 v2, s8, v14
	v_min_i32_e32 v3, s9, v2
	v_cmp_lt_i32_e32 vcc, -1, v2
	s_lshl_b32 s8, s85, 5
	s_movk_i32 s9, 0xc0
	v_cndmask_b32_e32 v2, 0, v3, vcc
	v_add_u32_e32 v2, s7, v2
	v_ashrrev_i32_e32 v3, 31, v2
	v_lshlrev_b64 v[2:3], 6, v[2:3]
	v_lshl_add_u64 v[2:3], v[2:3], 0, s[4:5]
	v_or_b32_e32 v2, v2, v144
	v_lshlrev_b64 v[2:3], 1, v[2:3]
	s_add_i32 s4, s6, s7
	v_lshl_add_u64 v[4:5], s[58:59], 0, v[2:3]
	v_lshl_add_u64 v[2:3], s[60:61], 0, v[2:3]
	s_add_i32 s4, s4, s8
	global_load_dwordx4 v[120:123], v[4:5], off
	global_load_dwordx4 v[124:127], v[2:3], off
	v_add_u32_e32 v2, s4, v7
	v_ashrrev_i32_e32 v3, 31, v2
	s_add_u32 s0, s40, s0
	s_addc_u32 s1, s41, s1
	v_lshlrev_b64 v[2:3], 7, v[2:3]
	v_lshl_add_u64 v[2:3], s[0:1], 0, v[2:3]
; #define ATTN_QLOAD(W) do { const bf16_t* qr_ = Qb + ((size_t)((W).b * 24 + (W).hd) * SEQ + (size_t)((W).r * (W).L + (W).i0 + 32 * wave + l31)) * 64; \
;         _Pragma("unroll") for (int ks_ = 0; ks_ < 4; ++ks_) qv[ks_] = *(const u32x4*)(qr_ + 16 * ks_ + 8 * h); } while (0)
; template <bool FUSED> __device__ __forceinline__ void attn_phase(const Args& a, LAS unsigned char* lds, int tid, int lane, int wave) {
;     ...
;     const int h = lane >> 5, l31 = lane & 31;
;     const int q = (lane & 15) >> 2, p = lane & 3, blk = (lane >> 4) & 1;
;     int u = blockIdx.x;
;     u32x4 kv[6], vv[6], qv[4];
;     ...
;     if (u < NU) { const AUnit w0 = attn_decode(u, HD0, NH); attn_issue(w0, Qb, Kb, Vb, tid, wave, lane, kv, vv); ATTN_QLOAD(w0); }
;     while (u < NU) {
;         const AUnit w = attn_decode(u, HD0, NH);
;         const int hd = w.hd, slot = hd & 7, L = w.L, i0 = w.i0;
;         const int iq = i0 + 32 * wave + l31; const size_t tq = (size_t)w.b * SEQ + (size_t)iq * w.dil + w.r;
;         bf16_t* qrow = Qb + ((size_t)(w.b * 24 + hd) * SEQ + (size_t)(w.r * L + iq)) * 64;
	v_lshl_add_u64 v[2:3], v[148:149], 1, v[2:3]
	global_load_dwordx4 v[88:91], v[2:3], off
	global_load_dwordx4 v[92:95], v[2:3], off offset:32
	global_load_dwordx4 v[100:103], v[2:3], off offset:64
	global_load_dwordx4 v[108:111], v[2:3], off offset:96
	v_mbcnt_hi_u32_b32 v2, -1, v187
	v_and_b32_e32 v4, 64, v2
	v_xor_b32_e32 v3, 32, v2
	v_add_u32_e32 v4, 64, v4
	v_cmp_lt_i32_e32 vcc, v3, v4
	v_lshlrev_b32_e32 v4, 3, v0
	s_lshl_b32 s0, s85, 12
	v_cndmask_b32_e32 v2, v2, v3, vcc
	v_lshlrev_b32_e32 v153, 2, v2
	v_lshlrev_b32_e32 v2, 2, v8
	v_sub_u32_e32 v175, v2, v7
	v_and_or_b32 v3, v6, 3, v2
	v_lshlrev_b32_e32 v2, 1, v0
	v_and_b32_e32 v2, 32, v2
	v_and_b32_e32 v6, 24, v4
	v_add3_u32 v16, 0, v2, v6
	v_lshlrev_b32_e32 v2, 6, v7
	s_add_i32 s0, s0, 0
	v_sub_co_u32_e32 v150, vcc, 0, v2
	s_add_i32 s6, s0, 0x1f800
	s_nop 0
	v_subb_co_u32_e64 v151, s[0:1], 0, 0, vcc
	v_and_b32_e32 v6, 8, v0
	v_cmp_eq_u32_e64 s[0:1], 0, v6
	v_add_u32_e32 v6, s8, v3
	s_add_i32 s10, s8, 32
	s_movk_i32 s7, 0x90
	v_mul_lo_u32 v25, v6, s9
	v_or_b32_e32 v6, s10, v7
	v_mul_lo_u32 v26, v6, s7
	v_add_u32_e32 v6, s10, v3
	s_add_i32 s10, s8, 64
	v_mul_lo_u32 v27, v6, s9
	v_or_b32_e32 v6, s10, v7
	v_mul_lo_u32 v28, v6, s7
	v_add_u32_e32 v6, s10, v3
	s_add_i32 s10, s8, 0x60
	v_or_b32_e32 v145, s8, v7
	v_mul_lo_u32 v29, v6, s9
	v_or_b32_e32 v6, s10, v7
	s_addk_i32 s8, 0x80
	v_mul_lo_u32 v30, v6, s7
	v_add_u32_e32 v6, s10, v3
	v_add_u32_e32 v3, s8, v3
	v_mul_lo_u32 v33, v3, s9
	v_bitop3_b32 v3, v8, v0, 15 bitop3:0x78
	v_lshlrev_b32_e32 v34, 3, v3
	v_add_u32_e32 v3, 2, v8
	v_bitop3_b32 v3, v3, v0, 15 bitop3:0x78
	v_lshlrev_b32_e32 v35, 3, v3
	v_add_u32_e32 v3, 4, v8
	v_bitop3_b32 v3, v3, v0, 15 bitop3:0x78
	v_lshlrev_b32_e32 v36, 3, v3
	v_add_u32_e32 v3, 6, v8
	v_bitop3_b32 v3, v3, v0, 15 bitop3:0x78
	v_lshlrev_b32_e32 v37, 3, v3
	v_add_u32_e32 v3, 8, v8
	v_bitop3_b32 v3, v3, v0, 15 bitop3:0x78
	v_lshlrev_b32_e32 v38, 3, v3
	v_add_u32_e32 v3, 10, v8
	v_bitop3_b32 v3, v3, v0, 15 bitop3:0x78
	v_lshlrev_b32_e32 v39, 3, v3
	v_add_u32_e32 v3, 12, v8
	v_bitop3_b32 v3, v3, v0, 15 bitop3:0x78
	v_lshlrev_b32_e32 v40, 3, v3
	v_add_u32_e32 v3, 14, v8
	v_ashrrev_i32_e32 v2, 3, v0
	v_bitop3_b32 v3, v3, v0, 15 bitop3:0x78
	v_lshlrev_b32_e32 v8, 3, v3
	v_lshrrev_b32_e32 v3, 1, v2
	v_xor_b32_e32 v3, v3, v0
	v_mul_lo_u32 v31, v6, s9
	v_or_b32_e32 v6, s8, v7
	v_lshlrev_b32_e32 v3, 4, v3
	v_mul_lo_u32 v32, v6, s7
	v_and_b32_e32 v42, 0x70, v3
	v_ashrrev_i32_e32 v3, 31, v2
	v_add_u32_e32 v6, 8, v2
	v_lshlrev_b64 v[156:157], 7, v[2:3]
	v_lshrrev_b32_e32 v3, 1, v6
	v_lshl_add_u32 v17, v7, 7, s6
	v_xor_b32_e32 v3, v3, v0
	v_ashrrev_i32_e32 v7, 31, v6
	v_lshl_add_u32 v41, v2, 7, s6
	v_lshl_add_u32 v43, v6, 7, s6
	v_lshlrev_b32_e32 v3, 4, v3
	v_lshlrev_b64 v[158:159], 7, v[6:7]
	v_add_u32_e32 v6, 16, v2
	v_add_u32_e32 v2, 24, v2
	v_and_b32_e32 v44, 0x70, v3
	v_lshrrev_b32_e32 v3, 1, v2
	v_cmp_gt_u32_e64 s[4:5], 32, v0
	v_xor_b32_e32 v0, v3, v0
	v_and_b32_e32 v1, 7, v1
	v_ashrrev_i32_e32 v7, 31, v6
	v_lshlrev_b32_e32 v0, 4, v0
	v_lshl_add_u32 v5, v1, 4, 0
	v_subrev_u32_e32 v155, 64, v9
	v_subrev_u32_e32 v170, 64, v10
	v_subrev_u32_e32 v171, 64, v11
	v_subrev_u32_e32 v172, 64, v12
	v_subrev_u32_e32 v173, 64, v13
	v_subrev_u32_e32 v174, 64, v14
	v_and_b32_e32 v4, 56, v4
	v_mul_lo_u32 v18, v9, s7
	v_mul_lo_u32 v9, v9, s9
	v_mul_lo_u32 v19, v10, s7
	v_mul_lo_u32 v10, v10, s9
	v_mul_lo_u32 v20, v11, s7
	v_mul_lo_u32 v11, v11, s9
	v_mul_lo_u32 v21, v12, s7
	v_mul_lo_u32 v12, v12, s9
	v_mul_lo_u32 v22, v13, s7
	v_mul_lo_u32 v13, v13, s9
	v_mul_lo_u32 v23, v14, s7
	v_mul_lo_u32 v14, v14, s9
	v_mul_lo_u32 v24, v145, s7
	v_lshl_add_u32 v45, v6, 7, s6
	v_lshlrev_b64 v[160:161], 7, v[6:7]
	v_lshl_add_u32 v6, v2, 7, s6
	v_and_b32_e32 v0, 0x70, v0
	v_ashrrev_i32_e32 v3, 31, v2
	v_lshlrev_b32_e32 v146, 5, v1
	s_movk_i32 s74, 0x60
	v_lshlrev_b64 v[162:163], 7, v[2:3]
	v_lshl_add_u64 v[164:165], s[44:45], 0, v[146:147]
	v_lshl_add_u64 v[166:167], v[148:149], 2, s[42:43]
	v_mov_b32_e32 v176, 0x358637bd
	v_add_u32_e32 v177, v5, v18
	v_add_u32_e32 v188, v5, v9
	v_add_u32_e32 v189, v5, v19
	v_add_u32_e32 v190, v5, v10
	v_add_u32_e32 v191, v5, v20
	v_add_u32_e32 v192, v5, v11
	v_add_u32_e32 v193, v5, v21
	v_add_u32_e32 v194, v5, v12
	v_add_u32_e32 v195, v5, v22
	v_add_u32_e32 v196, v5, v13
	v_add_u32_e32 v197, v5, v23
	v_add_u32_e32 v198, v5, v14
	v_add_u32_e32 v199, v15, v24
	v_add_u32_e32 v200, v16, v25
	v_add_u32_e32 v201, v15, v26
	v_add_u32_e32 v202, v16, v27
	v_add_u32_e32 v203, v15, v28
	v_add_u32_e32 v204, v16, v29
	v_add_u32_e32 v205, v15, v30
	v_add_u32_e32 v206, v16, v31
	v_add_u32_e32 v207, v15, v32
	v_add_u32_e32 v208, v16, v33
	v_add_u32_e32 v209, v17, v34
	v_add_u32_e32 v210, v17, v35
	v_add_u32_e32 v211, v17, v36
	v_add_u32_e32 v212, v17, v37
	v_add_u32_e32 v213, v17, v38
	v_add_u32_e32 v214, v17, v39
	v_add_u32_e32 v215, v17, v40
	v_add_u32_e32 v216, v17, v8
	v_lshlrev_b32_e32 v146, 1, v4
	v_add_u32_e32 v217, v41, v42
	v_add_u32_e32 v218, v43, v44
	v_add_u32_e32 v219, v45, v42
	v_add_u32_e32 v220, v6, v0
	v_mov_b32_e32 v221, 0xf149f2ca
	s_mov_b32 s67, s93
	s_branch .LBB0_280

; #define ATTN_QLOAD(W) do { const bf16_t* qr_ = Qb + ((size_t)((W).b * 24 + (W).hd) * SEQ + (size_t)((W).r * (W).L + (W).i0 + 32 * wave + l31)) * 64; \
;         _Pragma("unroll") for (int ks_ = 0; ks_ < 4; ++ks_) qv[ks_] = *(const u32x4*)(qr_ + 16 * ks_ + 8 * h); } while (0)
; __device__ __forceinline__ void attn_issue(const AUnit& w, const bf16_t* Qb, const bf16_t* Kb, const bf16_t* Vb, int tid, int wave, int lane, u32x4 (&kv)[6], u32x4 (&vv)[6]) {
;     const int ch = tid & 7;
; #pragma unroll
;     for (int i = 0; i < 6; ++i) { const int row = (tid + 512 * i) >> 3; int pk = w.i0 - 64 + row; pk = pk < 0 ? 0 : (pk >= w.L ? w.L - 1 : pk);
;         const size_t off = ((size_t)(w.b * 24 + w.hd) * SEQ + (size_t)(w.r * w.L + pk)) * 64 + ch * 8; kv[i] = *(const u32x4*)(Kb + off); vv[i] = *(const u32x4*)(Vb + off); }
; }
; template <bool FUSED> __device__ __forceinline__ void attn_phase(const Args& a, LAS unsigned char* lds, int tid, int lane, int wave) {
;     ...
;     if (u < NU) { const AUnit w0 = attn_decode(u, HD0, NH); attn_issue(w0, Qb, Kb, Vb, tid, wave, lane, kv, vv); ATTN_QLOAD(w0); }
.LBB0_399:
	v_mov_b32_e32 v0, v178
	s_cmpk_lt_i32 s2, 0x800
	s_cbranch_scc0 .LBB0_408
	s_and_b32 s93, s2, 7
	s_lshl_b32 s93, s93, 5
	s_bfe_u32 s94, s2, 0x50003
	s_or_b32 s93, s93, s94
	s_andn2_b32 s94, s2, 0xff
	s_or_b32 s93, s93, s94
	s_cmpk_eq_i32 s54, 0x100
	s_cselect_b32 s93, s93, s2
	s_ashr_i32 s1, s93, 5
	s_lshr_b32 s4, s1, 29
	s_add_i32 s4, s1, s4
	s_and_b32 s4, s4, -8
	s_sub_i32 s1, s1, s4
	s_ashr_i32 s5, s1, 2
	s_and_b32 s5, s5, -2
	s_lshr_b32 s6, 32, s5
	s_and_b32 s0, s93, 31
	s_lshr_b32 s7, 0x2000, s5
	s_sub_i32 s5, 5, s5
	s_add_i32 s6, s6, -1
	s_lshr_b32 s5, s0, s5
	s_and_b32 s0, s6, s0
	s_ashr_i32 s4, s93, 31
	s_lshl_b32 s6, s0, 8
	s_lshr_b32 s4, s4, 24
	v_lshlrev_b32_e32 v2, 3, v0
	v_ashrrev_i32_e32 v7, 3, v0
	s_sub_i32 s8, s6, 64
	s_add_i32 s4, s93, s4
	v_and_b32_e32 v144, 56, v2
	v_add_u32_e32 v2, s8, v7
	s_add_i32 s9, s7, -1
	s_ashr_i32 s4, s4, 8
	v_min_i32_e32 v3, s9, v2
	v_cmp_lt_i32_e32 vcc, -1, v2
	s_mul_i32 s0, s4, 24
	s_mul_i32 s7, s5, s7
	v_cndmask_b32_e32 v2, 0, v3, vcc
	s_add_i32 s0, s0, s1
	v_add_u32_e32 v2, s7, v2
	s_ashr_i32 s1, s0, 31
	v_ashrrev_i32_e32 v3, 31, v2
	s_lshl_b64 s[4:5], s[0:1], 19
	v_lshlrev_b64 v[2:3], 6, v[2:3]
	v_lshl_add_u64 v[2:3], v[2:3], 0, s[4:5]
	v_or_b32_e32 v2, v2, v144
	v_lshlrev_b64 v[2:3], 1, v[2:3]
	v_lshl_add_u64 v[4:5], s[58:59], 0, v[2:3]
	v_lshl_add_u64 v[2:3], s[60:61], 0, v[2:3]
	global_load_dwordx4 v[64:67], v[4:5], off
	global_load_dwordx4 v[68:71], v[2:3], off
	v_add_u32_e32 v2, 0x200, v0
	v_ashrrev_i32_e32 v8, 3, v2
	v_add_u32_e32 v2, s8, v8
	v_min_i32_e32 v3, s9, v2
	v_cmp_lt_i32_e32 vcc, -1, v2
	s_lshl_b32 s48, s85, 5
	v_and_b32_e32 v145, 31, v186
	v_cndmask_b32_e32 v2, 0, v3, vcc
	v_add_u32_e32 v2, s7, v2
	v_ashrrev_i32_e32 v3, 31, v2
	v_lshlrev_b64 v[2:3], 6, v[2:3]
	v_lshl_add_u64 v[2:3], v[2:3], 0, s[4:5]
	v_or_b32_e32 v2, v2, v144
	v_lshlrev_b64 v[2:3], 1, v[2:3]
	v_lshl_add_u64 v[4:5], s[58:59], 0, v[2:3]
	v_lshl_add_u64 v[2:3], s[60:61], 0, v[2:3]
	global_load_dwordx4 v[72:75], v[4:5], off
	global_load_dwordx4 v[76:79], v[2:3], off
	v_add_u32_e32 v2, 0x400, v0
	v_ashrrev_i32_e32 v9, 3, v2
	v_add_u32_e32 v2, s8, v9
	v_min_i32_e32 v3, s9, v2
	v_cmp_lt_i32_e32 vcc, -1, v2
	s_lshl_b64 s[0:1], s[0:1], 20
	v_ashrrev_i32_e32 v6, 5, v186
	v_cndmask_b32_e32 v2, 0, v3, vcc
	v_add_u32_e32 v2, s7, v2
	v_ashrrev_i32_e32 v3, 31, v2
	v_lshlrev_b64 v[2:3], 6, v[2:3]
	v_lshl_add_u64 v[2:3], v[2:3], 0, s[4:5]
	v_or_b32_e32 v2, v2, v144
	v_lshlrev_b64 v[2:3], 1, v[2:3]
	v_lshl_add_u64 v[4:5], s[58:59], 0, v[2:3]
	v_lshl_add_u64 v[2:3], s[60:61], 0, v[2:3]
	global_load_dwordx4 v[80:83], v[4:5], off
	global_load_dwordx4 v[84:87], v[2:3], off
	v_add_u32_e32 v2, 0x600, v0
	v_ashrrev_i32_e32 v10, 3, v2
	v_add_u32_e32 v2, s8, v10
	v_min_i32_e32 v3, s9, v2
	v_cmp_lt_i32_e32 vcc, -1, v2
	v_lshlrev_b32_e32 v148, 3, v6
	v_ashrrev_i32_e32 v149, 31, v148
	v_cndmask_b32_e32 v2, 0, v3, vcc
	v_add_u32_e32 v2, s7, v2
	v_ashrrev_i32_e32 v3, 31, v2
	v_lshlrev_b64 v[2:3], 6, v[2:3]
	v_lshl_add_u64 v[2:3], v[2:3], 0, s[4:5]
	v_or_b32_e32 v2, v2, v144
	v_lshlrev_b64 v[2:3], 1, v[2:3]
	v_lshl_add_u64 v[4:5], s[58:59], 0, v[2:3]
	v_lshl_add_u64 v[2:3], s[60:61], 0, v[2:3]
	global_load_dwordx4 v[88:91], v[4:5], off
	global_load_dwordx4 v[92:95], v[2:3], off
	v_add_u32_e32 v2, 0x800, v0
	v_ashrrev_i32_e32 v11, 3, v2
	v_add_u32_e32 v2, s8, v11
	v_min_i32_e32 v3, s9, v2
	v_cmp_lt_i32_e32 vcc, -1, v2
	v_lshrrev_b32_e32 v1, 2, v186
	v_ashrrev_i32_e32 v188, 3, v186
	v_cndmask_b32_e32 v2, 0, v3, vcc
	v_add_u32_e32 v2, s7, v2
	v_ashrrev_i32_e32 v3, 31, v2
	v_lshlrev_b64 v[2:3], 6, v[2:3]
	v_lshl_add_u64 v[2:3], v[2:3], 0, s[4:5]
	v_or_b32_e32 v2, v2, v144
	v_lshlrev_b64 v[2:3], 1, v[2:3]
	v_lshl_add_u64 v[4:5], s[58:59], 0, v[2:3]
	v_lshl_add_u64 v[2:3], s[60:61], 0, v[2:3]
	global_load_dwordx4 v[112:115], v[4:5], off
	global_load_dwordx4 v[116:119], v[2:3], off
	v_add_u32_e32 v2, 0xa00, v0
	v_ashrrev_i32_e32 v12, 3, v2
	v_add_u32_e32 v2, s8, v12
	v_min_i32_e32 v3, s9, v2
	v_cmp_lt_i32_e32 vcc, -1, v2
	v_lshlrev_b32_e32 v29, 9, v188
	v_add_u32_e32 v190, 8, v188
	v_cndmask_b32_e32 v2, 0, v3, vcc
	v_add_u32_e32 v2, s7, v2
	v_ashrrev_i32_e32 v3, 31, v2
	v_lshlrev_b64 v[2:3], 6, v[2:3]
	v_lshl_add_u64 v[2:3], v[2:3], 0, s[4:5]
	v_or_b32_e32 v2, v2, v144
	v_lshlrev_b64 v[2:3], 1, v[2:3]
	s_add_i32 s4, s6, s7
	v_lshl_add_u64 v[4:5], s[58:59], 0, v[2:3]
	v_lshl_add_u64 v[2:3], s[60:61], 0, v[2:3]
	s_add_i32 s4, s4, s48
	global_load_dwordx4 v[120:123], v[4:5], off
	global_load_dwordx4 v[124:127], v[2:3], off
	v_add_u32_e32 v2, s4, v145
	v_ashrrev_i32_e32 v3, 31, v2
	s_add_u32 s0, s40, s0
	s_addc_u32 s1, s41, s1
	v_lshlrev_b64 v[2:3], 7, v[2:3]
	v_lshl_add_u64 v[2:3], s[0:1], 0, v[2:3]
	v_lshl_add_u64 v[2:3], v[148:149], 1, v[2:3]
	global_load_dwordx4 v[96:99], v[2:3], off
	global_load_dwordx4 v[100:103], v[2:3], off offset:32
	global_load_dwordx4 v[104:107], v[2:3], off offset:64
	global_load_dwordx4 v[108:111], v[2:3], off offset:96
	v_and_b32_e32 v2, 7, v0
	v_mbcnt_hi_u32_b32 v0, -1, v187
	v_and_b32_e32 v5, 64, v0
	v_xor_b32_e32 v4, 32, v0
	v_add_u32_e32 v5, 64, v5
	v_cmp_lt_i32_e32 vcc, v4, v5
	v_lshlrev_b32_e32 v5, 3, v186
	s_add_i32 s10, s48, 32
	v_cndmask_b32_e32 v0, v0, v4, vcc
	v_lshlrev_b32_e32 v151, 2, v0
	v_lshlrev_b32_e32 v0, 2, v6
	v_sub_u32_e32 v177, v0, v145
	v_and_or_b32 v1, v1, 3, v0
	v_lshlrev_b32_e32 v0, 1, v186
	s_lshl_b32 s0, s85, 7
	v_and_b32_e32 v0, 32, v0
	v_and_b32_e32 v13, 24, v5
	v_or_b32_e32 v22, s10, v145
	v_add_u32_e32 v23, s10, v1
	s_add_i32 s10, s48, 64
	v_and_b32_e32 v158, 0x1e00, v29
	v_lshlrev_b32_e32 v29, 9, v190
	v_add_u32_e32 v192, 24, v188
	s_add_i32 s4, s0, 0
	v_add3_u32 v13, 0, v0, v13
	v_lshlrev_b32_e32 v0, 11, v188
	s_lshl_b32 s0, s85, 12
	v_or_b32_e32 v24, s10, v145
	v_add_u32_e32 v25, s10, v1
	s_add_i32 s10, s48, 0x60
	v_and_b32_e32 v160, 0x1e00, v29
	v_lshlrev_b32_e32 v29, 9, v192
	s_waitcnt vmcnt(16)
; #define LAS __attribute__((address_space(3)))
; template <bool FUSED> __device__ __forceinline__ void attn_phase(const Args& a, LAS unsigned char* lds, int tid, int lane, int wave) {
;     ...
;             const int ch = tid & 7;
;             const f32x4 g0 = *(const f32x4*)(a.kw + hd * 64 + ch * 8), g1 = *(const f32x4*)(a.kw + hd * 64 + ch * 8 + 4);
; #pragma unroll
;             for (int i = 0; i < 6; ++i) { const int row = (tid + 512 * i) >> 3;
;                 const float e0 = bflo(kv[i].x), e1 = bfhi(kv[i].x), e2 = bflo(kv[i].y), e3 = bfhi(kv[i].y), e4 = bflo(kv[i].z), e5 = bfhi(kv[i].z), e6 = bflo(kv[i].w), e7 = bfhi(kv[i].w);
;                 float ss = (e0 * e0 + e1 * e1) + (e2 * e2 + e3 * e3) + (e4 * e4 + e5 * e5) + (e6 * e6 + e7 * e7);
;                 ss += dpp_movf<0xB1>(ss); ss += dpp_movf<0x4E>(ss); ss += dpp_movf<0x141>(ss);
;                 const float rk = __builtin_amdgcn_rsqf(ss * (1.f / 64.f) + 1e-6f);
;                 u32x4 wv; wv.x = pk2(e0 * rk * g0.x, e1 * rk * g0.y); wv.y = pk2(e2 * rk * g0.z, e3 * rk * g0.w); wv.z = pk2(e4 * rk * g1.x, e5 * rk * g1.y); wv.w = pk2(e6 * rk * g1.z, e7 * rk * g1.w);
;                 *(LAS u32x4*)(lds + row * KP + ch * 16) = wv;
;                 *(LAS u32x4*)(lds + LDS_VOFF + row * VP + ch * 16) = vv[i];
;     ...
;                 for (int it = 0; it < 4; ++it) { const int r = 8 * it + (lane >> 3), c16 = lane & 7, t = i0 + 32 * wave + r; const size_t tokg = (size_t)w.b * SEQ + t;
;                     fl1[it] = LSE[tokg * 24 + 8 + slot]; fl2[it] = LSE[tokg * 24 + 16 + slot];
;                     fo1[it] = __builtin_nontemporal_load((const u32x4*)(Qb + ((size_t)(w.b * 24 + 8 + slot) * SEQ + (t & 3) * 2048 + (t >> 2)) * 64 + c16 * 8));
;                     fo2[it] = __builtin_nontemporal_load((const u32x4*)(Qb + ((size_t)(w.b * 24 + 16 + slot) * SEQ + (t & 15) * 512 + (t >> 4)) * 64 + c16 * 8));
;                     fg[it] = __builtin_nontemporal_load((const u32x4*)(Gb + tokg * 1024 + 512 + slot * 64 + c16 * 8)); }
;             }
;             LAS unsigned char* ost = lds + 129024 + wave * 4096;
; #pragma unroll
;             for (int dt = 0; dt < 2; ++dt)
; #pragma unroll
;                 for (int ig = 0; ig < 4; ++ig) { u32x2 wv; wv.x = pk2(o[dt][4 * ig] * inv, o[dt][4 * ig + 1] * inv); wv.y = pk2(o[dt][4 * ig + 2] * inv, o[dt][4 * ig + 3] * inv);
	v_lshrrev_b32_e32 v37, 1, v188
	v_lshrrev_b32_e32 v39, 1, v190
	v_lshrrev_b32_e32 v42, 1, v192
	v_lshl_add_u32 v4, v6, 4, 0
	v_and_b32_e32 v150, 0x1800, v0
	v_and_b32_e32 v0, 56, v5
	s_add_i32 s0, s0, 0
	v_or_b32_e32 v26, s10, v145
	v_add_u32_e32 v27, s10, v1
	s_add_i32 s10, s48, 0x80
	v_and_b32_e32 v162, 0x1e00, v29
	v_bitop3_b32 v29, v6, v186, 15 bitop3:0x78
	v_add_u32_e32 v30, 2, v6
	v_add_u32_e32 v31, 4, v6
	v_add_u32_e32 v32, 6, v6
	v_add_u32_e32 v33, 8, v6
	v_add_u32_e32 v34, 10, v6
	v_add_u32_e32 v35, 12, v6
	v_add_u32_e32 v6, 14, v6
	v_xor_b32_e32 v37, v37, v186
	v_xor_b32_e32 v39, v39, v186
	v_xor_b32_e32 v42, v42, v186
	v_mov_b32_e32 v147, 0
	v_or_b32_e32 v187, s48, v145
	v_lshlrev_b32_e32 v146, 1, v0
	s_add_i32 s6, s0, 0x1f800
	v_and_b32_e32 v14, 8, v186
	s_movk_i32 s8, 0x90
	s_movk_i32 s9, 0xc0
	v_add_u32_e32 v21, s48, v1
	v_or_b32_e32 v28, s10, v145
	v_add_u32_e32 v1, s10, v1
	v_add_u32_e32 v191, 16, v188
	v_bitop3_b32 v30, v30, v186, 15 bitop3:0x78
	v_bitop3_b32 v31, v31, v186, 15 bitop3:0x78
	v_bitop3_b32 v32, v32, v186, 15 bitop3:0x78
	v_bitop3_b32 v33, v33, v186, 15 bitop3:0x78
	v_bitop3_b32 v34, v34, v186, 15 bitop3:0x78
	v_bitop3_b32 v35, v35, v186, 15 bitop3:0x78
	v_bitop3_b32 v6, v6, v186, 15 bitop3:0x78
	v_lshlrev_b32_e32 v37, 4, v37
	v_lshlrev_b32_e32 v39, 4, v39
	v_lshlrev_b32_e32 v42, 4, v42
	v_lshl_add_u32 v3, v2, 4, 0
	v_subrev_u32_e32 v153, 64, v7
	v_subrev_u32_e32 v155, 64, v8
	v_subrev_u32_e32 v159, 64, v9
	v_subrev_u32_e32 v161, 64, v10
	v_subrev_u32_e32 v163, 64, v11
	v_subrev_u32_e32 v176, 64, v12
	v_lshl_add_u64 v[156:157], s[40:41], 0, v[146:147]
	v_lshl_add_u32 v5, v145, 7, s6
	s_add_i32 s7, s4, 0x27810
	v_cmp_eq_u32_e64 s[4:5], 0, v14
	v_mul_lo_u32 v14, v7, s8
	v_mul_lo_u32 v7, v7, s9
	v_mul_lo_u32 v15, v8, s8
	v_mul_lo_u32 v8, v8, s9
	v_mul_lo_u32 v16, v9, s8
	v_mul_lo_u32 v9, v9, s9
	v_mul_lo_u32 v17, v10, s8
	v_mul_lo_u32 v10, v10, s9
	v_mul_lo_u32 v18, v11, s8
	v_mul_lo_u32 v11, v11, s9
	v_mul_lo_u32 v19, v12, s8
	v_mul_lo_u32 v12, v12, s9
	v_mul_lo_u32 v20, v187, s8
	v_mul_lo_u32 v21, v21, s9
	v_mul_lo_u32 v22, v22, s8
	v_mul_lo_u32 v23, v23, s9
	v_mul_lo_u32 v24, v24, s8
	v_mul_lo_u32 v25, v25, s9
	v_mul_lo_u32 v26, v26, s8
	v_mul_lo_u32 v27, v27, s9
	v_mul_lo_u32 v28, v28, s8
	v_mul_lo_u32 v1, v1, s9
	v_lshlrev_b32_e32 v29, 3, v29
	v_lshlrev_b32_e32 v30, 3, v30
	v_lshlrev_b32_e32 v31, 3, v31
	v_lshlrev_b32_e32 v32, 3, v32
	v_lshlrev_b32_e32 v33, 3, v33
	v_lshlrev_b32_e32 v34, 3, v34
	v_lshlrev_b32_e32 v35, 3, v35
	v_lshlrev_b32_e32 v6, 3, v6
	v_lshl_add_u32 v36, v188, 7, s6
	v_and_b32_e32 v37, 0x70, v37
	v_lshl_add_u32 v38, v190, 7, s6
	v_and_b32_e32 v39, 0x70, v39
	v_lshl_add_u32 v40, v191, 7, s6
	v_lshl_add_u32 v41, v192, 7, s6
	v_and_b32_e32 v42, 0x70, v42
	v_lshlrev_b32_e32 v146, 5, v2
	s_mov_b32 s47, 0
	v_cmp_gt_u32_e64 s[0:1], 32, v186
	v_lshl_add_u32 v189, v186, 2, s7
	s_movk_i32 s49, 0x60
	v_lshl_add_u32 v193, v188, 2, s7
	v_lshl_add_u64 v[164:165], s[44:45], 0, v[146:147]
	v_lshl_add_u64 v[166:167], v[148:149], 2, s[42:43]
	v_mov_b32_e32 v186, 0x358637bd
	v_add_u32_e32 v194, v3, v14
	v_add_u32_e32 v195, v3, v7
	v_add_u32_e32 v196, v3, v15
	v_add_u32_e32 v197, v3, v8
	v_add_u32_e32 v198, v3, v16
	v_add_u32_e32 v199, v3, v9
	v_add_u32_e32 v200, v3, v17
	v_add_u32_e32 v201, v3, v10
	v_add_u32_e32 v202, v3, v18
	v_add_u32_e32 v203, v3, v11
	v_add_u32_e32 v204, v3, v19
	v_add_u32_e32 v205, v3, v12
	v_add_u32_e32 v206, v4, v20
	v_add_u32_e32 v207, v13, v21
	v_add_u32_e32 v208, v4, v22
	v_add_u32_e32 v209, v13, v23
	v_add_u32_e32 v210, v4, v24
	v_add_u32_e32 v211, v13, v25
	v_add_u32_e32 v212, v4, v26
	v_add_u32_e32 v213, v13, v27
	v_add_u32_e32 v214, v4, v28
	v_add_u32_e32 v215, v13, v1
	s_mov_b32 s56, 0x12000000
	v_add_u32_e32 v216, v5, v29
	v_add_u32_e32 v217, v5, v30
	v_add_u32_e32 v218, v5, v31
	v_add_u32_e32 v219, v5, v32
	v_add_u32_e32 v220, v5, v33
	v_add_u32_e32 v221, v5, v34
	v_add_u32_e32 v222, v5, v35
	v_add_u32_e32 v223, v5, v6
	v_add_u32_e32 v224, v36, v37
	v_lshlrev_b32_e32 v146, 1, v0
	s_mov_b32 s57, 0xa000000
	v_add_u32_e32 v225, v38, v39
	v_add_u32_e32 v226, v40, v37
	v_add_u32_e32 v227, v41, v42
	v_mov_b32_e32 v228, 0xf149f2ca
	s_mov_b32 s46, s93
	s_branch .LBB0_402

; #define LAS __attribute__((address_space(3)))
; __global__ void __launch_bounds__(512, 2) mega_fwd(Args a) {
;     extern __shared__ __attribute__((aligned(16))) unsigned char lds_raw[];
;     LAS unsigned char* lds = (LAS unsigned char*)lds_raw;
;     cg::grid_group grid = cg::this_grid();
;     const int tid = threadIdx.x, lane = tid & 63, wave = __builtin_amdgcn_readfirstlane(tid >> 6);
	.amdhsa_kernel _Z8mega_fwd4Args
		.amdhsa_group_segment_fixed_size 0
		.amdhsa_private_segment_fixed_size 0
		.amdhsa_kernarg_size 328
		.amdhsa_user_sgpr_count 2
		.amdhsa_user_sgpr_dispatch_ptr 0
		.amdhsa_user_sgpr_queue_ptr 0
		.amdhsa_user_sgpr_kernarg_segment_ptr 1
		.amdhsa_user_sgpr_dispatch_id 0
		.amdhsa_user_sgpr_kernarg_preload_length 0
		.amdhsa_user_sgpr_kernarg_preload_offset 0
		.amdhsa_user_sgpr_private_segment_size 0
		.amdhsa_uses_dynamic_stack 0
		.amdhsa_enable_private_segment 0
		.amdhsa_system_sgpr_workgroup_id_x 1
		.amdhsa_system_sgpr_workgroup_id_y 0
		.amdhsa_system_sgpr_workgroup_id_z 0
		.amdhsa_system_sgpr_workgroup_info 0
		.amdhsa_system_vgpr_workitem_id 2
		.amdhsa_next_free_vgpr 243
		.amdhsa_next_free_sgpr 96
		.amdhsa_accum_offset 244
		.amdhsa_reserve_vcc 1
		.amdhsa_float_round_mode_32 0
		.amdhsa_float_round_mode_16_64 0
		.amdhsa_float_denorm_mode_32 3
		.amdhsa_float_denorm_mode_16_64 3
		.amdhsa_dx10_clamp 1
		.amdhsa_ieee_mode 1
		.amdhsa_fp16_overflow 0
		.amdhsa_tg_split 0
		.amdhsa_exception_fp_ieee_invalid_op 0
		.amdhsa_exception_fp_denorm_src 0
		.amdhsa_exception_fp_ieee_div_zero 0
		.amdhsa_exception_fp_ieee_overflow 0
		.amdhsa_exception_fp_ieee_underflow 0
		.amdhsa_exception_fp_ieee_inexact 0
		.amdhsa_exception_int_div_zero 0
	.end_amdhsa_kernel

; #define LAS __attribute__((address_space(3)))
; __global__ void __launch_bounds__(512, 2) mega_fwd(Args a) {
;     extern __shared__ __attribute__((aligned(16))) unsigned char lds_raw[];
;     LAS unsigned char* lds = (LAS unsigned char*)lds_raw;
;     cg::grid_group grid = cg::this_grid();
;     const int tid = threadIdx.x, lane = tid & 63, wave = __builtin_amdgcn_readfirstlane(tid >> 6);
amdhsa.kernels:
  - .agpr_count:     0
    .args:
      - .offset:         0
        .size:           72
        .value_kind:     by_value
      - .offset:         72
        .size:           4
        .value_kind:     hidden_block_count_x
      - .offset:         76
        .size:           4
        .value_kind:     hidden_block_count_y
      - .offset:         80
        .size:           4
        .value_kind:     hidden_block_count_z
      - .offset:         84
        .size:           2
        .value_kind:     hidden_group_size_x
      - .offset:         86
        .size:           2
        .value_kind:     hidden_group_size_y
      - .offset:         88
        .size:           2
        .value_kind:     hidden_group_size_z
      - .offset:         90
        .size:           2
        .value_kind:     hidden_remainder_x
      - .offset:         92
        .size:           2
        .value_kind:     hidden_remainder_y
      - .offset:         94
        .size:           2
        .value_kind:     hidden_remainder_z
      - .offset:         112
        .size:           8
        .value_kind:     hidden_global_offset_x
      - .offset:         120
        .size:           8
        .value_kind:     hidden_global_offset_y
      - .offset:         128
        .size:           8
        .value_kind:     hidden_global_offset_z
      - .offset:         136
        .size:           2
        .value_kind:     hidden_grid_dims
      - .offset:         160
        .size:           8
        .value_kind:     hidden_multigrid_sync_arg
      - .offset:         192
        .size:           4
        .value_kind:     hidden_dynamic_lds_size
    .group_segment_fixed_size: 0
    .kernarg_segment_align: 8
    .kernarg_segment_size: 328
    .language:       OpenCL C
    .language_version:
      - 2
      - 0
    .max_flat_workgroup_size: 512
    .name:           _Z8mega_fwd4Args
    .private_segment_fixed_size: 0
    .sgpr_count:     102
    .sgpr_spill_count: 0
    .symbol:         _Z8mega_fwd4Args.kd
    .uniform_work_group_size: 1
    .uses_dynamic_stack: false
    .vgpr_count:     243
    .vgpr_spill_count: 0
    .wavefront_size: 64
